# attention: steady-state rescale threshold and floor set once in the rescale path instead of after every tile
# baseline (speedup 1.0000x reference)
.Lat2_back_8:
	v_exp_f32_e32 v64, v64
	v_exp_f32_e32 v65, v65
	v_exp_f32_e32 v66, v66
	v_exp_f32_e32 v67, v67
	v_exp_f32_e32 v68, v68
	v_exp_f32_e32 v69, v69
	v_exp_f32_e32 v70, v70
	v_exp_f32_e32 v71, v71
	v_pk_add_f32 v[232:233], v[232:233], v[64:65]
	v_pk_add_f32 v[234:235], v[234:235], v[66:67]
	v_pk_add_f32 v[232:233], v[232:233], v[68:69]
	v_pk_add_f32 v[234:235], v[234:235], v[70:71]
	v_cvt_pk_bf16_f32 v64, v64, v65
	v_cvt_pk_bf16_f32 v65, v66, v67
	v_cvt_pk_bf16_f32 v66, v68, v69
	v_cvt_pk_bf16_f32 v67, v70, v71
	s_waitcnt lgkmcnt(0)
	s_nop 0
	v_mfma_f32_32x32x16_bf16 v[0:15], v[64:67], v[164:167], v[0:15]
	v_exp_f32_e32 v72, v72
	v_exp_f32_e32 v73, v73
	v_mfma_f32_32x32x16_bf16 v[16:31], v[64:67], v[168:171], v[16:31]
	ds_read_b64_tr_b16 v[164:165], v206 offset:2048
	ds_read_b64_tr_b16 v[166:167], v206 offset:2560
	v_exp_f32_e32 v74, v74
	v_exp_f32_e32 v75, v75
	v_pk_add_f32 v[232:233], v[232:233], v[72:73]
	v_mfma_f32_32x32x16_bf16 v[32:47], v[64:67], v[172:175], v[32:47]
	ds_read_b64_tr_b16 v[168:169], v206 offset:6144
	ds_read_b64_tr_b16 v[170:171], v206 offset:6656
	v_exp_f32_e32 v76, v76
	v_exp_f32_e32 v77, v77
	v_pk_add_f32 v[234:235], v[234:235], v[74:75]
	v_mfma_f32_32x32x16_bf16 v[48:63], v[64:67], v[176:179], v[48:63]
	ds_read_b64_tr_b16 v[172:173], v206 offset:10240
	ds_read_b64_tr_b16 v[174:175], v206 offset:10752
	v_exp_f32_e32 v78, v78
	v_exp_f32_e32 v79, v79
	v_pk_add_f32 v[232:233], v[232:233], v[76:77]
	v_pk_add_f32 v[234:235], v[234:235], v[78:79]
	v_cvt_pk_bf16_f32 v72, v72, v73
	v_cvt_pk_bf16_f32 v73, v74, v75
	v_cvt_pk_bf16_f32 v74, v76, v77
	v_cvt_pk_bf16_f32 v75, v78, v79
	s_nop 1
	v_mfma_f32_32x32x16_bf16 v[0:15], v[72:75], v[180:183], v[0:15]
	ds_read_b64_tr_b16 v[176:177], v206 offset:14336
	ds_read_b64_tr_b16 v[178:179], v206 offset:14848
	v_exp_f32_e32 v80, v80
	v_exp_f32_e32 v81, v81
	v_mfma_f32_32x32x16_bf16 v[16:31], v[72:75], v[184:187], v[16:31]
	ds_read_b64_tr_b16 v[180:181], v206 offset:3072
	ds_read_b64_tr_b16 v[182:183], v206 offset:3584
	v_exp_f32_e32 v82, v82
	v_exp_f32_e32 v83, v83
	v_pk_add_f32 v[232:233], v[232:233], v[80:81]
	v_mfma_f32_32x32x16_bf16 v[32:47], v[72:75], v[188:191], v[32:47]
	ds_read_b64_tr_b16 v[184:185], v206 offset:7168
	ds_read_b64_tr_b16 v[186:187], v206 offset:7680
	v_exp_f32_e32 v84, v84
	v_exp_f32_e32 v85, v85
	v_pk_add_f32 v[234:235], v[234:235], v[82:83]
	v_mfma_f32_32x32x16_bf16 v[48:63], v[72:75], v[192:195], v[48:63]
	ds_read_b64_tr_b16 v[188:189], v206 offset:11264
	ds_read_b64_tr_b16 v[190:191], v206 offset:11776
	v_exp_f32_e32 v86, v86
	v_exp_f32_e32 v87, v87
	v_pk_add_f32 v[232:233], v[232:233], v[84:85]
	v_pk_add_f32 v[234:235], v[234:235], v[86:87]
	v_cvt_pk_bf16_f32 v80, v80, v81
	v_cvt_pk_bf16_f32 v81, v82, v83
	v_cvt_pk_bf16_f32 v82, v84, v85
	v_cvt_pk_bf16_f32 v83, v86, v87
	s_nop 1
	s_waitcnt lgkmcnt(12)
	v_mfma_f32_32x32x16_bf16 v[0:15], v[80:83], v[164:167], v[0:15]
	ds_read_b64_tr_b16 v[192:193], v206 offset:15360
	ds_read_b64_tr_b16 v[194:195], v206 offset:15872
	v_exp_f32_e32 v88, v88
	v_exp_f32_e32 v89, v89
	s_waitcnt lgkmcnt(12)
	v_mfma_f32_32x32x16_bf16 v[16:31], v[80:83], v[168:171], v[16:31]
	v_exp_f32_e32 v90, v90
	v_exp_f32_e32 v91, v91
	v_pk_add_f32 v[232:233], v[232:233], v[88:89]
	s_waitcnt lgkmcnt(10)
	v_mfma_f32_32x32x16_bf16 v[32:47], v[80:83], v[172:175], v[32:47]
	v_exp_f32_e32 v92, v92
	v_exp_f32_e32 v93, v93
	v_pk_add_f32 v[234:235], v[234:235], v[90:91]
	s_waitcnt lgkmcnt(8)
	v_mfma_f32_32x32x16_bf16 v[48:63], v[80:83], v[176:179], v[48:63]
	v_exp_f32_e32 v94, v94
	v_exp_f32_e32 v95, v95
	v_pk_add_f32 v[232:233], v[232:233], v[92:93]
	v_pk_add_f32 v[234:235], v[234:235], v[94:95]
	v_cvt_pk_bf16_f32 v88, v88, v89
	v_cvt_pk_bf16_f32 v89, v90, v91
	v_cvt_pk_bf16_f32 v90, v92, v93
	v_cvt_pk_bf16_f32 v91, v94, v95
	s_nop 1
	s_waitcnt lgkmcnt(6)
	v_mfma_f32_32x32x16_bf16 v[0:15], v[88:91], v[180:183], v[0:15]
	s_waitcnt lgkmcnt(4)
	v_mfma_f32_32x32x16_bf16 v[16:31], v[88:91], v[184:187], v[16:31]
	s_waitcnt lgkmcnt(2)
	v_mfma_f32_32x32x16_bf16 v[32:47], v[88:91], v[188:191], v[32:47]
	s_waitcnt lgkmcnt(0)
	v_mfma_f32_32x32x16_bf16 v[48:63], v[88:91], v[192:195], v[48:63]
	s_mov_b32 s4, s59
	s_mov_b32 s59, s60
	s_mov_b32 s60, s61
	s_mov_b32 s61, s25
	s_mov_b32 s25, s4
	s_add_i32 s45, s45, 1
	s_waitcnt vmcnt(6)

.Lat2_allmasked_19:
	s_mov_b32 s4, s59
	s_mov_b32 s59, s60
	s_mov_b32 s60, s61
	s_mov_b32 s61, s25
	s_mov_b32 s25, s4
	s_add_i32 s45, s45, 1
	s_nop 0
	s_add_i32 s6, s45, 2
	s_cmp_lt_u32 s6, s39
	s_cbranch_scc1 .Lat2_w6_26
	s_cmp_eq_u32 s6, s39
	s_cbranch_scc1 .Lat2_w3_24
	s_waitcnt vmcnt(0)
	s_branch .Lat2_wd_25

.Lat2_resc_7:
	v_max_f32_e32 v212, s47, v214
	v_add_f32_e32 v210, v210, v212
	v_exp_f32_e64 v217, -v212
	v_sub_f32_e32 v64, v64, v212
	v_sub_f32_e32 v65, v65, v212
	v_sub_f32_e32 v66, v66, v212
	v_sub_f32_e32 v67, v67, v212
	v_sub_f32_e32 v68, v68, v212
	v_sub_f32_e32 v69, v69, v212
	v_sub_f32_e32 v70, v70, v212
	v_sub_f32_e32 v71, v71, v212
	v_sub_f32_e32 v72, v72, v212
	v_sub_f32_e32 v73, v73, v212
	v_sub_f32_e32 v74, v74, v212
	v_sub_f32_e32 v75, v75, v212
	v_sub_f32_e32 v76, v76, v212
	v_sub_f32_e32 v77, v77, v212
	v_sub_f32_e32 v78, v78, v212
	v_sub_f32_e32 v79, v79, v212
	v_sub_f32_e32 v80, v80, v212
	v_sub_f32_e32 v81, v81, v212
	v_sub_f32_e32 v82, v82, v212
	v_sub_f32_e32 v83, v83, v212
	v_sub_f32_e32 v84, v84, v212
	v_sub_f32_e32 v85, v85, v212
	v_sub_f32_e32 v86, v86, v212
	v_sub_f32_e32 v87, v87, v212
	v_sub_f32_e32 v88, v88, v212
	v_sub_f32_e32 v89, v89, v212
	v_sub_f32_e32 v90, v90, v212
	v_sub_f32_e32 v91, v91, v212
	v_sub_f32_e32 v92, v92, v212
	v_sub_f32_e32 v93, v93, v212
	v_sub_f32_e32 v94, v94, v212
	v_sub_f32_e32 v95, v95, v212
	v_sub_f32_e32 v100, 0, v210
	v_sub_f32_e32 v101, 0, v210
	v_sub_f32_e32 v102, 0, v210
	v_sub_f32_e32 v103, 0, v210
	v_sub_f32_e32 v104, 0, v210
	v_sub_f32_e32 v105, 0, v210
	v_sub_f32_e32 v106, 0, v210
	v_sub_f32_e32 v107, 0, v210
	v_sub_f32_e32 v108, 0, v210
	v_sub_f32_e32 v109, 0, v210
	v_sub_f32_e32 v110, 0, v210
	v_sub_f32_e32 v111, 0, v210
	v_sub_f32_e32 v112, 0, v210
	v_sub_f32_e32 v113, 0, v210
	v_sub_f32_e32 v114, 0, v210
	v_sub_f32_e32 v115, 0, v210
	v_mul_f32_e32 v232, v232, v217
	v_mul_f32_e32 v233, v233, v217
	v_mul_f32_e32 v234, v234, v217
	v_mul_f32_e32 v235, v235, v217
	s_waitcnt lgkmcnt(0)
	ds_write_b32 v220, v217
	s_waitcnt lgkmcnt(0)
	ds_read_b128 v[116:119], v221 offset:0
	ds_read_b128 v[120:123], v221 offset:32
	ds_read_b128 v[124:127], v221 offset:64
	ds_read_b128 v[128:131], v221 offset:96
	s_waitcnt lgkmcnt(0)
	v_mul_f32_e32 v0, v0, v116
	v_mul_f32_e32 v1, v1, v117
	v_mul_f32_e32 v2, v2, v118
	v_mul_f32_e32 v3, v3, v119
	v_mul_f32_e32 v4, v4, v120
	v_mul_f32_e32 v5, v5, v121
	v_mul_f32_e32 v6, v6, v122
	v_mul_f32_e32 v7, v7, v123
	v_mul_f32_e32 v8, v8, v124
	v_mul_f32_e32 v9, v9, v125
	v_mul_f32_e32 v10, v10, v126
	v_mul_f32_e32 v11, v11, v127
	v_mul_f32_e32 v12, v12, v128
	v_mul_f32_e32 v13, v13, v129
	v_mul_f32_e32 v14, v14, v130
	v_mul_f32_e32 v15, v15, v131
	v_mul_f32_e32 v16, v16, v116
	v_mul_f32_e32 v17, v17, v117
	v_mul_f32_e32 v18, v18, v118
	v_mul_f32_e32 v19, v19, v119
	v_mul_f32_e32 v20, v20, v120
	v_mul_f32_e32 v21, v21, v121
	v_mul_f32_e32 v22, v22, v122
	v_mul_f32_e32 v23, v23, v123
	v_mul_f32_e32 v24, v24, v124
	v_mul_f32_e32 v25, v25, v125
	v_mul_f32_e32 v26, v26, v126
	v_mul_f32_e32 v27, v27, v127
	v_mul_f32_e32 v28, v28, v128
	v_mul_f32_e32 v29, v29, v129
	v_mul_f32_e32 v30, v30, v130
	v_mul_f32_e32 v31, v31, v131
	v_mul_f32_e32 v32, v32, v116
	v_mul_f32_e32 v33, v33, v117
	v_mul_f32_e32 v34, v34, v118
	v_mul_f32_e32 v35, v35, v119
	v_mul_f32_e32 v36, v36, v120
	v_mul_f32_e32 v37, v37, v121
	v_mul_f32_e32 v38, v38, v122
	v_mul_f32_e32 v39, v39, v123
	v_mul_f32_e32 v40, v40, v124
	v_mul_f32_e32 v41, v41, v125
	v_mul_f32_e32 v42, v42, v126
	v_mul_f32_e32 v43, v43, v127
	v_mul_f32_e32 v44, v44, v128
	v_mul_f32_e32 v45, v45, v129
	v_mul_f32_e32 v46, v46, v130
	v_mul_f32_e32 v47, v47, v131
	v_mul_f32_e32 v48, v48, v116
	v_mul_f32_e32 v49, v49, v117
	v_mul_f32_e32 v50, v50, v118
	v_mul_f32_e32 v51, v51, v119
	v_mul_f32_e32 v52, v52, v120
	v_mul_f32_e32 v53, v53, v121
	v_mul_f32_e32 v54, v54, v122
	v_mul_f32_e32 v55, v55, v123
	v_mul_f32_e32 v56, v56, v124
	v_mul_f32_e32 v57, v57, v125
	v_mul_f32_e32 v58, v58, v126
	v_mul_f32_e32 v59, v59, v127
	v_mul_f32_e32 v60, v60, v128
	v_mul_f32_e32 v61, v61, v129
	v_mul_f32_e32 v62, v62, v130
	v_mul_f32_e32 v63, v63, v131
	s_mov_b32 s62, 0x41000000
	s_mov_b32 s47, 0
	s_branch .Lat2_back_8
